# LN3: waves 4-7 start their row loop ~2.7us later (s_sleep) so the two waves of a SIMD alternate between memory wait and compute
# baseline (speedup 1.0000x reference)
; __global__ void __launch_bounds__(NT, 2) fwd(const Args args) {
;     ...
;         if (IN(pb + 10)) { PHASE_BEGIN
;             const float* g = A.in[17] + ((size_t)L * 3 + 2) * D; const float* bb = A.in[18] + ((size_t)L * 3 + 2) * D; const bf16* X = WSP(bf16, WS_XB);
;             if (L + 1 < DEPTH) { stage_wig(A, F, L + 1); __syncthreads(); }
;             int m0, m1; row_range(F, m0, m1);
;             for (int m = m0; m < m1; m += 4) { u32x4 r[4][2];
; #pragma unroll
;                 for (int q = 0; q < 4; ++q) { const int mm = (m + q < m1) ? m + q : m1 - 1; row_raw(X + (size_t)mm * D, F.lane, r[q]); }
.LBB0_1693:
	v_mov_b32_e32 v1, s6
	v_lshl_add_u32 v1, s8, 3, v1
	v_readlane_b32 s12, v253, 53
	v_readlane_b32 s8, v253, 52
	s_nop 0
	v_min_i32_e32 v3, s12, v1
	v_mul_lo_u32 v4, s8, v1
	v_readfirstlane_b32 s11, v3
	v_readfirstlane_b32 s16, v4
	v_add_u32_e32 v3, v4, v3
	v_mov_b32_e32 v4, s8
	v_cmp_gt_i32_e32 vcc, s12, v1
	v_readfirstlane_b32 s6, v3
	s_nop 0
	v_addc_co_u32_e32 v1, vcc, v3, v4, vcc
	v_cmp_ge_i32_e32 vcc, v3, v1
	s_and_b64 s[12:13], vcc, exec
	v_readfirstlane_b32 s8, v1
	s_cbranch_scc1 .LBB0_1723
	s_mul_hi_i32 s12, s10, 0x3000
	s_mulk_i32 s10, 0x3000
	s_add_u32 s10, s10, 0x2000
	s_addc_u32 s12, s12, 0
	v_lshlrev_b32_e32 v4, 3, v0
	s_waitcnt lgkmcnt(0)
	s_add_u32 s14, s40, s10
	v_ashrrev_i32_e32 v5, 31, v4
	s_addc_u32 s15, s41, s12
	v_lshlrev_b64 v[6:7], 1, v[4:5]
	s_add_u32 s18, s42, s10
	v_lshl_add_u64 v[8:9], s[58:59], 0, v[6:7]
	s_mov_b64 s[26:27], 0xb880000
	s_addc_u32 s19, s43, s12
	v_lshl_add_u64 v[52:53], v[8:9], 0, s[26:27]
	v_lshlrev_b64 v[54:55], 2, v[4:5]
	s_mul_hi_i32 s13, s7, 0x6820
	s_mul_i32 s26, s7, 0x6820
	s_ashr_i32 s7, s6, 31
	s_add_i32 s12, s8, -1
	v_lshl_add_u64 v[56:57], s[14:15], 0, v[54:55]
	s_lshl_b64 s[14:15], s[6:7], 12
	s_add_u32 s14, s56, s14
	v_lshl_add_u64 v[58:59], s[18:19], 0, v[54:55]
	s_addc_u32 s15, s57, s15
	s_lshl_b64 s[18:19], s[6:7], 5
	v_ashrrev_i32_e32 v1, 31, v0
	s_add_u32 s18, s18, 0x1b000000
	s_addc_u32 s19, s19, 0
	v_lshlrev_b64 v[4:5], 2, v[0:1]
	v_lshl_add_u64 v[60:61], s[18:19], 0, v[4:5]
	s_lshl_b64 s[18:19], s[6:7], 11
	s_add_i32 s7, s11, s16
	s_add_i32 s10, s7, 3
	s_ashr_i32 s11, s10, 31
	s_lshl_b64 s[16:17], s[10:11], 5
	s_add_u32 s16, s16, 0x1b000000
	s_addc_u32 s17, s17, 0
	s_add_i32 s28, s7, 1
	v_lshl_add_u64 v[64:65], s[16:17], 0, v[4:5]
	s_lshl_b64 s[16:17], s[10:11], 11
	s_ashr_i32 s29, s28, 31
	v_lshl_add_u64 v[66:67], s[16:17], 0, v[6:7]
	s_lshl_b64 s[16:17], s[28:29], 12
	s_add_u32 s16, s56, s16
	s_addc_u32 s17, s57, s17
	s_lshl_b64 s[10:11], s[10:11], 12
	v_lshl_add_u64 v[62:63], s[18:19], 0, v[6:7]
	s_add_u32 s18, s56, s10
	s_addc_u32 s19, s57, s11
	s_add_i32 s10, s7, 2
	s_ashr_i32 s11, s10, 31
	s_lshl_b64 s[34:35], s[10:11], 5
	s_add_u32 s34, s34, 0x1b000000
	s_addc_u32 s35, s35, 0
	v_lshl_add_u64 v[68:69], s[34:35], 0, v[4:5]
	s_lshl_b64 s[34:35], s[10:11], 11
	v_lshl_add_u64 v[70:71], s[34:35], 0, v[6:7]
	s_lshl_b64 s[34:35], s[28:29], 11
	s_lshl_b64 s[10:11], s[10:11], 12
	v_lshl_add_u64 v[72:73], s[34:35], 0, v[6:7]
	s_add_u32 s34, s56, s10
	s_addc_u32 s35, s57, s11
	s_lshl_b64 s[10:11], s[28:29], 5
	s_add_u32 s10, s10, 0x1b000000
	s_addc_u32 s11, s11, 0
	v_lshlrev_b32_e32 v3, 5, v0
	v_cmp_gt_i32_e64 s[38:39], 8, v0
	v_cmp_eq_u32_e64 s[40:41], 1, v0
	v_cmp_eq_u32_e64 s[42:43], 2, v0
	v_cmp_eq_u32_e64 s[44:45], 3, v0
	v_cmp_eq_u32_e64 s[46:47], 4, v0
	v_cmp_eq_u32_e64 s[48:49], 5, v0
	v_cmp_eq_u32_e64 s[50:51], 6, v0
	v_cmp_eq_u32_e64 s[52:53], 7, v0
	v_lshl_add_u64 v[74:75], s[10:11], 0, v[4:5]
	v_readlane_b32 s10, v253, 11
	s_nop 3
	s_cmp_lt_u32 s10, 4
	s_cbranch_scc1 .Lwres_nosleep
	s_sleep 100
.Lwres_nosleep:
	s_and_b64 vcc, exec, s[4:5]
	s_cbranch_vccnz .Lwres_skip
	s_load_dwordx2 s[66:67], s[2:3], 0x50
	v_add_u32_e32 v198, 0x12000, v3
	ds_read_b128 v[94:97], v198 offset:0
	ds_read_b128 v[98:101], v198 offset:16
	ds_read_b128 v[102:105], v198 offset:2048
	ds_read_b128 v[106:109], v198 offset:2064
	ds_read_b128 v[110:113], v198 offset:4096
	ds_read_b128 v[114:117], v198 offset:4112
	ds_read_b128 v[118:121], v198 offset:6144
	ds_read_b128 v[122:125], v198 offset:6160
	s_waitcnt lgkmcnt(0)
	ds_read_b128 v[126:129], v198 offset:8192
	ds_read_b128 v[130:133], v198 offset:8208
	ds_read_b128 v[134:137], v198 offset:10240
	ds_read_b128 v[138:141], v198 offset:10256
	ds_read_b128 v[142:145], v198 offset:12288
	ds_read_b128 v[146:149], v198 offset:12304
	ds_read_b128 v[150:153], v198 offset:14336
	ds_read_b128 v[154:157], v198 offset:14352
	s_waitcnt lgkmcnt(0)
	ds_read_b128 v[158:161], v198 offset:16384
	ds_read_b128 v[162:165], v198 offset:16400
	ds_read_b128 v[166:169], v198 offset:18432
	ds_read_b128 v[170:173], v198 offset:18448
	ds_read_b128 v[174:177], v198 offset:20480
	ds_read_b128 v[178:181], v198 offset:20496
	ds_read_b128 v[182:185], v198 offset:22528
	ds_read_b128 v[186:189], v198 offset:22544
	s_waitcnt lgkmcnt(0)
	ds_read_b128 v[190:193], v198 offset:24576
	ds_read_b128 v[194:197], v198 offset:24592
	ds_read_b128 v[202:205], v198 offset:26624
	ds_read_b128 v[206:209], v198 offset:26640
	ds_read_b128 v[210:213], v198 offset:28672
	ds_read_b128 v[214:217], v198 offset:28688
	ds_read_b128 v[218:221], v198 offset:30720
	ds_read_b128 v[222:225], v198 offset:30736
	s_waitcnt lgkmcnt(0)
	s_add_u32 s66, s66, s26
	s_addc_u32 s67, s67, s13
	s_add_u32 s66, s66, 0x3000
	s_addc_u32 s67, s67, 0
	v_lshl_add_u64 v[198:199], v[0:1], 2, s[66:67]
	global_load_dword v200, v[198:199], off
